# speedup vs baseline: 1.0048x; 1.0028x over previous
; #define PG8_STAGE(bufoff, gbase, voff) do { _Pragma("unroll") for (int _i = 0; _i < 2; ++_i) \
;         __builtin_amdgcn_global_load_lds((const unsigned*)((const char*)(gbase) + (voff)[_i]), (LAS unsigned*)(lds + (bufoff) + ldsw + _i * 8192), 16, 0, 0); } while (0)
; #define PG8_LDA(dst, b, h) do { _Pragma("unroll") for (int m = 0; m < 4; ++m) _Pragma("unroll") for (int k = 0; k < 2; ++k) dst[m][k] = *(const LAS bf16x8*)(lds + PG8_SA(b, h) + aoff + m * 2048 + k * 1024); } while (0)
; #define PG8_LDB(dst, b, h) do { _Pragma("unroll") for (int n = 0; n < 2; ++n) _Pragma("unroll") for (int k = 0; k < 2; ++k) dst[n][k] = *(const LAS bf16x8*)(lds + PG8_SB(b, h) + boff + n * 2048 + k * 1024); } while (0)
; #define PG8_MMA(ai, bj, At, Bt) do { __builtin_amdgcn_s_setprio(1); _Pragma("unroll") for (int m = 0; m < 4; ++m) _Pragma("unroll") for (int n = 0; n < 2; ++n) _Pragma("unroll") for (int k = 0; k < 2; ++k) \
;         acc[ai][bj][m][n] = __builtin_amdgcn_mfma_f32_16x16x32_bf16(Bt[n][k], At[m][k], acc[ai][bj][m][n], 0, 0, 0); __builtin_amdgcn_s_setprio(0); } while (0)
; #define PG8_WAIT_V(n) asm volatile("s_waitcnt vmcnt(" #n ")" ::: "memory")
; #define PG8_WAIT_L(n) asm volatile("s_waitcnt lgkmcnt(" #n ")" ::: "memory")
; #define PG8_BAR __builtin_amdgcn_s_barrier()
; #define PG8_SCHED __builtin_amdgcn_sched_barrier(0)
; __device__ __forceinline__ void gemm_phase(LAS unsigned char* lds, const GemmD& g) {
;     ...
;             PG8_LDB(B1, 0, 1); PG8_STAGE(PG8_SB(0, 0), b2, voffB);
;             PG8_BAR; PG8_WAIT_L(0); PG8_MMA(0, 1, At, B1); PG8_BAR;
;             PG8_LDA(At, 0, 1); PG8_STAGE(PG8_SA(0, 0), a2, voffA);
;             PG8_BAR; PG8_WAIT_L(0); PG8_MMA(1, 0, At, B0); PG8_BAR; PG8_SCHED;
;             PG8_STAGE(PG8_SB(0, 1), b2 + hstep, voffB);
;             PG8_WAIT_V(6); PG8_BAR; PG8_MMA(1, 1, At, B1); PG8_BAR;
;             PG8_LDB(B0, 1, 0); PG8_SCHED; PG8_LDA(At, 1, 0); PG8_STAGE(PG8_SA(0, 1), a2 + hstep, voffA);
;             PG8_WAIT_L(8); PG8_BAR; PG8_WAIT_L(0); PG8_MMA(0, 0, At, B0); PG8_BAR; PG8_SCHED;
.Lkl_ptr_done:
	s_add_i32 s4, 0, 0x14000
	s_add_i32 s6, s6, s87
	s_mov_b32 m0, s6
	ds_read_b128 v[204:207], v245
	ds_read_b128 v[208:211], v245 offset:1024
	ds_read_b128 v[234:237], v245 offset:2048
	ds_read_b128 v[238:241], v245 offset:3072
	global_load_lds_dwordx4 v172, s[100:101]
	s_add_i32 m0, s6, 0x2000
	s_nop 0
	global_load_lds_dwordx4 v168, s[100:101]
	s_barrier
	s_waitcnt lgkmcnt(0)
	v_mfma_f32_16x16x32_bf16 v[118:121], v[204:207], v[152:155], v[118:121]
	v_mfma_f32_16x16x32_bf16 v[114:117], v[234:237], v[152:155], v[114:117]
	v_mfma_f32_16x16x32_bf16 v[102:105], v[204:207], v[160:163], v[102:105]
	v_mfma_f32_16x16x32_bf16 v[98:101], v[234:237], v[160:163], v[98:101]
	v_mfma_f32_16x16x32_bf16 v[86:89], v[204:207], v[188:191], v[86:89]
	v_mfma_f32_16x16x32_bf16 v[82:85], v[234:237], v[188:191], v[82:85]
	v_mfma_f32_16x16x32_bf16 v[70:73], v[204:207], v[196:199], v[70:73]
	v_mfma_f32_16x16x32_bf16 v[66:69], v[234:237], v[196:199], v[66:69]
	v_mfma_f32_16x16x32_bf16 v[118:121], v[208:211], v[156:159], v[118:121]
	v_mfma_f32_16x16x32_bf16 v[114:117], v[238:241], v[156:159], v[114:117]
	v_mfma_f32_16x16x32_bf16 v[102:105], v[208:211], v[184:187], v[102:105]
	v_mfma_f32_16x16x32_bf16 v[98:101], v[238:241], v[184:187], v[98:101]
	v_mfma_f32_16x16x32_bf16 v[86:89], v[208:211], v[192:195], v[86:89]
	v_mfma_f32_16x16x32_bf16 v[82:85], v[238:241], v[192:195], v[82:85]
	v_mfma_f32_16x16x32_bf16 v[70:73], v[208:211], v[200:203], v[70:73]
	v_mfma_f32_16x16x32_bf16 v[66:69], v[238:241], v[200:203], v[66:69]
	s_barrier
	s_mov_b32 m0, s2
	ds_read_b128 v[152:155], v233 offset:16384
	ds_read_b128 v[156:159], v233 offset:17408
	ds_read_b128 v[160:163], v233 offset:18432
	ds_read_b128 v[184:187], v233 offset:19456
	ds_read_b128 v[188:191], v233 offset:20480
	ds_read_b128 v[192:195], v233 offset:21504
	ds_read_b128 v[196:199], v233 offset:22528
	ds_read_b128 v[200:203], v233 offset:23552
	global_load_lds_dwordx4 v170, s[98:99]
	s_mov_b32 m0, s3
	s_nop 0
	global_load_lds_dwordx4 v166, s[98:99]
	s_barrier
	s_waitcnt lgkmcnt(0)
	v_mfma_f32_16x16x32_bf16 v[62:65], v[136:139], v[152:155], v[62:65]
	v_mfma_f32_16x16x32_bf16 v[58:61], v[144:147], v[152:155], v[58:61]
	v_mfma_f32_16x16x32_bf16 v[46:49], v[136:139], v[160:163], v[46:49]
	v_mfma_f32_16x16x32_bf16 v[42:45], v[144:147], v[160:163], v[42:45]
	v_mfma_f32_16x16x32_bf16 v[30:33], v[136:139], v[188:191], v[30:33]
	v_mfma_f32_16x16x32_bf16 v[26:29], v[144:147], v[188:191], v[26:29]
	v_mfma_f32_16x16x32_bf16 v[14:17], v[136:139], v[196:199], v[14:17]
	v_mfma_f32_16x16x32_bf16 v[10:13], v[144:147], v[196:199], v[10:13]
	v_mfma_f32_16x16x32_bf16 v[62:65], v[140:143], v[156:159], v[62:65]
	v_mfma_f32_16x16x32_bf16 v[58:61], v[148:151], v[156:159], v[58:61]
	v_mfma_f32_16x16x32_bf16 v[46:49], v[140:143], v[184:187], v[46:49]
	v_mfma_f32_16x16x32_bf16 v[42:45], v[148:151], v[184:187], v[42:45]
	v_mfma_f32_16x16x32_bf16 v[30:33], v[140:143], v[192:195], v[30:33]
	v_mfma_f32_16x16x32_bf16 v[26:29], v[148:151], v[192:195], v[26:29]
	v_mfma_f32_16x16x32_bf16 v[14:17], v[140:143], v[200:203], v[14:17]
	v_mfma_f32_16x16x32_bf16 v[10:13], v[148:151], v[200:203], v[10:13]
	s_barrier
	s_add_i32 s4, s4, s87
	s_mov_b32 m0, s4
	s_nop 0
	global_load_lds_dwordx4 v242, s[100:101]
	s_add_i32 m0, s4, 0x2000
	s_nop 0
	global_load_lds_dwordx4 v243, s[100:101]
	s_waitcnt vmcnt(6)
	s_barrier
	v_mfma_f32_16x16x32_bf16 v[54:57], v[204:207], v[152:155], v[54:57]
	v_mfma_f32_16x16x32_bf16 v[50:53], v[234:237], v[152:155], v[50:53]
	v_mfma_f32_16x16x32_bf16 v[38:41], v[204:207], v[160:163], v[38:41]
	v_mfma_f32_16x16x32_bf16 v[34:37], v[234:237], v[160:163], v[34:37]
	v_mfma_f32_16x16x32_bf16 v[22:25], v[204:207], v[188:191], v[22:25]
	v_mfma_f32_16x16x32_bf16 v[18:21], v[234:237], v[188:191], v[18:21]
	v_mfma_f32_16x16x32_bf16 v[6:9], v[204:207], v[196:199], v[6:9]
	v_mfma_f32_16x16x32_bf16 v[2:5], v[234:237], v[196:199], v[2:5]
	v_mfma_f32_16x16x32_bf16 v[54:57], v[208:211], v[156:159], v[54:57]
	v_mfma_f32_16x16x32_bf16 v[50:53], v[238:241], v[156:159], v[50:53]
	v_mfma_f32_16x16x32_bf16 v[38:41], v[208:211], v[184:187], v[38:41]
	v_mfma_f32_16x16x32_bf16 v[34:37], v[238:241], v[184:187], v[34:37]
	v_mfma_f32_16x16x32_bf16 v[22:25], v[208:211], v[192:195], v[22:25]
	v_mfma_f32_16x16x32_bf16 v[18:21], v[238:241], v[192:195], v[18:21]
	v_mfma_f32_16x16x32_bf16 v[6:9], v[208:211], v[200:203], v[6:9]
	v_mfma_f32_16x16x32_bf16 v[2:5], v[238:241], v[200:203], v[2:5]
	s_barrier
	s_add_i32 s4, 0, 0x18000
	ds_read_b128 v[136:139], v246
	ds_read_b128 v[140:143], v246 offset:1024
	ds_read_b128 v[144:147], v246 offset:2048
	ds_read_b128 v[148:151], v246 offset:3072
	s_mov_b32 m0, s64
	ds_read_b128 v[152:155], v233 offset:32768
	ds_read_b128 v[156:159], v233 offset:33792
	ds_read_b128 v[160:163], v233 offset:34816
	ds_read_b128 v[184:187], v233 offset:35840
	ds_read_b128 v[188:191], v233 offset:36864
	ds_read_b128 v[192:195], v233 offset:37888
	ds_read_b128 v[196:199], v233 offset:38912
	ds_read_b128 v[200:203], v233 offset:39936
	global_load_lds_dwordx4 v174, s[98:99]
	s_mov_b32 m0, s65
	s_nop 0
	global_load_lds_dwordx4 v176, s[98:99]
	s_waitcnt lgkmcnt(8)
	s_barrier
; #define PG8_STAGE(bufoff, gbase, voff) do { _Pragma("unroll") for (int _i = 0; _i < 2; ++_i) \
;         __builtin_amdgcn_global_load_lds((const unsigned*)((const char*)(gbase) + (voff)[_i]), (LAS unsigned*)(lds + (bufoff) + ldsw + _i * 8192), 16, 0, 0); } while (0)
; #define PG8_LDA(dst, b, h) do { _Pragma("unroll") for (int m = 0; m < 4; ++m) _Pragma("unroll") for (int k = 0; k < 2; ++k) dst[m][k] = *(const LAS bf16x8*)(lds + PG8_SA(b, h) + aoff + m * 2048 + k * 1024); } while (0)
; #define PG8_LDB(dst, b, h) do { _Pragma("unroll") for (int n = 0; n < 2; ++n) _Pragma("unroll") for (int k = 0; k < 2; ++k) dst[n][k] = *(const LAS bf16x8*)(lds + PG8_SB(b, h) + boff + n * 2048 + k * 1024); } while (0)
; #define PG8_MMA(ai, bj, At, Bt) do { __builtin_amdgcn_s_setprio(1); _Pragma("unroll") for (int m = 0; m < 4; ++m) _Pragma("unroll") for (int n = 0; n < 2; ++n) _Pragma("unroll") for (int k = 0; k < 2; ++k) \
;         acc[ai][bj][m][n] = __builtin_amdgcn_mfma_f32_16x16x32_bf16(Bt[n][k], At[m][k], acc[ai][bj][m][n], 0, 0, 0); __builtin_amdgcn_s_setprio(0); } while (0)
; #define PG8_WAIT_V(n) asm volatile("s_waitcnt vmcnt(" #n ")" ::: "memory")
; #define PG8_WAIT_L(n) asm volatile("s_waitcnt lgkmcnt(" #n ")" ::: "memory")
; #define PG8_BAR __builtin_amdgcn_s_barrier()
; #define PG8_SCHED __builtin_amdgcn_sched_barrier(0)
; __device__ __forceinline__ void gemm_epilogue(const GemmD& g, const f32x4 (&acc)[2][2][4][2], const Unit& u, int wr, int wc, int fr, int fq) {
;     const int row0 = u.pm * BM + wr * 64 + fr;
;     const int mode = g.mode;
;     if (u.part >= 0) {
; __device__ __forceinline__ void gemm_phase(LAS unsigned char* lds, const GemmD& g) {
;     ...
;             PG8_WAIT_L(8); PG8_BAR; PG8_WAIT_L(0); PG8_MMA(0, 0, At, B0); PG8_BAR; PG8_SCHED;
;             PG8_LDB(B1, 1, 1); PG8_STAGE(PG8_SB(1, 0), b3, voffB);
;             PG8_BAR; PG8_WAIT_L(0); PG8_MMA(0, 1, At, B1); PG8_BAR;
;             PG8_LDA(At, 1, 1); PG8_STAGE(PG8_SA(1, 0), a3, voffA);
;             PG8_BAR; PG8_WAIT_L(0); PG8_MMA(1, 0, At, B0); PG8_BAR; PG8_SCHED;
;             PG8_STAGE(PG8_SB(1, 1), b3 + hstep, voffB);
;             PG8_WAIT_V(6); PG8_BAR; PG8_MMA(1, 1, At, B1); PG8_BAR;
;         }
	s_waitcnt lgkmcnt(0)
	v_mfma_f32_16x16x32_bf16 v[126:129], v[136:139], v[152:155], v[126:129]
	v_mfma_f32_16x16x32_bf16 v[122:125], v[144:147], v[152:155], v[122:125]
	v_mfma_f32_16x16x32_bf16 v[110:113], v[136:139], v[160:163], v[110:113]
	v_mfma_f32_16x16x32_bf16 v[106:109], v[144:147], v[160:163], v[106:109]
	v_mfma_f32_16x16x32_bf16 v[94:97], v[136:139], v[188:191], v[94:97]
	v_mfma_f32_16x16x32_bf16 v[90:93], v[144:147], v[188:191], v[90:93]
	v_mfma_f32_16x16x32_bf16 v[78:81], v[136:139], v[196:199], v[78:81]
	v_mfma_f32_16x16x32_bf16 v[74:77], v[144:147], v[196:199], v[74:77]
	v_mfma_f32_16x16x32_bf16 v[126:129], v[140:143], v[156:159], v[126:129]
	v_mfma_f32_16x16x32_bf16 v[122:125], v[148:151], v[156:159], v[122:125]
	v_mfma_f32_16x16x32_bf16 v[110:113], v[140:143], v[184:187], v[110:113]
	v_mfma_f32_16x16x32_bf16 v[106:109], v[148:151], v[184:187], v[106:109]
	v_mfma_f32_16x16x32_bf16 v[94:97], v[140:143], v[192:195], v[94:97]
	v_mfma_f32_16x16x32_bf16 v[90:93], v[148:151], v[192:195], v[90:93]
	v_mfma_f32_16x16x32_bf16 v[78:81], v[140:143], v[200:203], v[78:81]
	v_mfma_f32_16x16x32_bf16 v[74:77], v[148:151], v[200:203], v[74:77]
	s_barrier
	s_add_u32 s98, s98, 0x80
	s_addc_u32 s99, s99, 0
	s_add_i32 s6, 0, 0x1c000
	s_add_i32 s4, s4, s87
	ds_read_b128 v[204:207], v247
	ds_read_b128 v[208:211], v247 offset:1024
	ds_read_b128 v[234:237], v247 offset:2048
	ds_read_b128 v[238:241], v247 offset:3072
	s_add_u32 s100, s100, 0x80
	s_addc_u32 s101, s101, 0
	s_mov_b32 m0, s4
	s_nop 0
	global_load_lds_dwordx4 v172, s[100:101]
	s_add_i32 m0, s4, 0x2000
	s_nop 0
	global_load_lds_dwordx4 v168, s[100:101]
	s_barrier
	s_waitcnt lgkmcnt(0)
	v_mfma_f32_16x16x32_bf16 v[118:121], v[204:207], v[152:155], v[118:121]
	v_mfma_f32_16x16x32_bf16 v[114:117], v[234:237], v[152:155], v[114:117]
	v_mfma_f32_16x16x32_bf16 v[102:105], v[204:207], v[160:163], v[102:105]
	v_mfma_f32_16x16x32_bf16 v[98:101], v[234:237], v[160:163], v[98:101]
	v_mfma_f32_16x16x32_bf16 v[86:89], v[204:207], v[188:191], v[86:89]
	v_mfma_f32_16x16x32_bf16 v[82:85], v[234:237], v[188:191], v[82:85]
	v_mfma_f32_16x16x32_bf16 v[70:73], v[204:207], v[196:199], v[70:73]
	v_mfma_f32_16x16x32_bf16 v[66:69], v[234:237], v[196:199], v[66:69]
	v_mfma_f32_16x16x32_bf16 v[118:121], v[208:211], v[156:159], v[118:121]
	v_mfma_f32_16x16x32_bf16 v[114:117], v[238:241], v[156:159], v[114:117]
	v_mfma_f32_16x16x32_bf16 v[102:105], v[208:211], v[184:187], v[102:105]
	v_mfma_f32_16x16x32_bf16 v[98:101], v[238:241], v[184:187], v[98:101]
	v_mfma_f32_16x16x32_bf16 v[86:89], v[208:211], v[192:195], v[86:89]
	v_mfma_f32_16x16x32_bf16 v[82:85], v[238:241], v[192:195], v[82:85]
	v_mfma_f32_16x16x32_bf16 v[70:73], v[208:211], v[200:203], v[70:73]
	v_mfma_f32_16x16x32_bf16 v[66:69], v[238:241], v[200:203], v[66:69]
	s_barrier
	s_mov_b32 m0, s28
	ds_read_b128 v[152:155], v233 offset:49152
	ds_read_b128 v[156:159], v233 offset:50176
	ds_read_b128 v[160:163], v233 offset:51200
	ds_read_b128 v[184:187], v233 offset:52224
	ds_read_b128 v[188:191], v233 offset:53248
	ds_read_b128 v[192:195], v233 offset:54272
	ds_read_b128 v[196:199], v233 offset:55296
	ds_read_b128 v[200:203], v233 offset:56320
	global_load_lds_dwordx4 v170, s[98:99]
	s_mov_b32 m0, s29
	s_nop 0
	global_load_lds_dwordx4 v166, s[98:99]
	s_barrier
	s_waitcnt lgkmcnt(0)
	v_mfma_f32_16x16x32_bf16 v[62:65], v[136:139], v[152:155], v[62:65]
	v_mfma_f32_16x16x32_bf16 v[58:61], v[144:147], v[152:155], v[58:61]
	v_mfma_f32_16x16x32_bf16 v[46:49], v[136:139], v[160:163], v[46:49]
	v_mfma_f32_16x16x32_bf16 v[42:45], v[144:147], v[160:163], v[42:45]
	v_mfma_f32_16x16x32_bf16 v[30:33], v[136:139], v[188:191], v[30:33]
	v_mfma_f32_16x16x32_bf16 v[26:29], v[144:147], v[188:191], v[26:29]
	v_mfma_f32_16x16x32_bf16 v[14:17], v[136:139], v[196:199], v[14:17]
	v_mfma_f32_16x16x32_bf16 v[10:13], v[144:147], v[196:199], v[10:13]
	v_mfma_f32_16x16x32_bf16 v[62:65], v[140:143], v[156:159], v[62:65]
	v_mfma_f32_16x16x32_bf16 v[58:61], v[148:151], v[156:159], v[58:61]
	v_mfma_f32_16x16x32_bf16 v[46:49], v[140:143], v[184:187], v[46:49]
	v_mfma_f32_16x16x32_bf16 v[42:45], v[148:151], v[184:187], v[42:45]
	v_mfma_f32_16x16x32_bf16 v[30:33], v[140:143], v[192:195], v[30:33]
	v_mfma_f32_16x16x32_bf16 v[26:29], v[148:151], v[192:195], v[26:29]
	v_mfma_f32_16x16x32_bf16 v[14:17], v[140:143], v[200:203], v[14:17]
	v_mfma_f32_16x16x32_bf16 v[10:13], v[148:151], v[200:203], v[10:13]
	s_barrier
	s_add_i32 s4, s6, s87
	s_mov_b32 m0, s4
	s_nop 0
	global_load_lds_dwordx4 v242, s[100:101]
	s_add_i32 m0, s4, 0x2000
	s_nop 0
	global_load_lds_dwordx4 v243, s[100:101]
	s_add_u32 s100, s100, 0x80
	s_addc_u32 s101, s101, 0
	s_mov_b32 s4, s5
	s_waitcnt vmcnt(6)
	s_barrier
	v_mfma_f32_16x16x32_bf16 v[54:57], v[204:207], v[152:155], v[54:57]
	v_mfma_f32_16x16x32_bf16 v[50:53], v[234:237], v[152:155], v[50:53]
	v_mfma_f32_16x16x32_bf16 v[38:41], v[204:207], v[160:163], v[38:41]
	v_mfma_f32_16x16x32_bf16 v[34:37], v[234:237], v[160:163], v[34:37]
	v_mfma_f32_16x16x32_bf16 v[22:25], v[204:207], v[188:191], v[22:25]
	v_mfma_f32_16x16x32_bf16 v[18:21], v[234:237], v[188:191], v[18:21]
	v_mfma_f32_16x16x32_bf16 v[6:9], v[204:207], v[196:199], v[6:9]
	v_mfma_f32_16x16x32_bf16 v[2:5], v[234:237], v[196:199], v[2:5]
	v_mfma_f32_16x16x32_bf16 v[54:57], v[208:211], v[156:159], v[54:57]
	v_mfma_f32_16x16x32_bf16 v[50:53], v[238:241], v[156:159], v[50:53]
	v_mfma_f32_16x16x32_bf16 v[38:41], v[208:211], v[184:187], v[38:41]
	v_mfma_f32_16x16x32_bf16 v[34:37], v[238:241], v[184:187], v[34:37]
	v_mfma_f32_16x16x32_bf16 v[22:25], v[208:211], v[192:195], v[22:25]
	v_mfma_f32_16x16x32_bf16 v[18:21], v[238:241], v[192:195], v[18:21]
	v_mfma_f32_16x16x32_bf16 v[6:9], v[208:211], v[200:203], v[6:9]
	v_mfma_f32_16x16x32_bf16 v[2:5], v[238:241], v[200:203], v[2:5]
	s_barrier
	s_cbranch_vccz .LBB0_145
	v_lshl_add_u32 v184, s56, 8, v228
	s_cmp_lt_i32 s66, 0
	s_mov_b64 s[4:5], -1
	s_cbranch_scc0 .LBB0_704
